# GEMM loops without per-segment s_setprio flips + SW attention sink values from a per-unit lane table (no load or vmcnt drain inside the tile loop; no extra SGPRs)
# speedup vs baseline: 1.0029x; 1.0029x over previous
; __device__ __forceinline__ float shx(float v, int lane, int m) { return __builtin_bit_cast(float, __builtin_amdgcn_ds_bpermute((lane ^ m) << 2, __builtin_bit_cast(int, v))); }
; __device__ __forceinline__ void unpack8(const v4u w, float* v) { v[0] = bf_lo(w.x); v[1] = bf_hi(w.x); v[2] = bf_lo(w.y); v[3] = bf_hi(w.y); v[4] = bf_lo(w.z); v[5] = bf_hi(w.z); v[6] = bf_lo(w.w); v[7] = bf_hi(w.w); }
; __device__ __forceinline__ void sw_attn(const bf16* QKV, const float* rope, const float* qg, const float* kg, const float* sinks, bf16* O, LAS unsigned char* lds, int tid) {
;     ...
;         SW_LOADQ(0);
;         {
;             const int row = tid >> 1, half = tid & 1, kpos = blk * 128 - 128 + row;
;             v4u outw[4];
;             if (kpos >= 0) {
;                 const bf16* kp = QKV + ((size_t)(b * 20 + 16 + kvh) * SEQ + kpos) * 64 + 32 * half;
;                 float v[32];
; #pragma unroll
;                 for (int c = 0; c < 4; ++c) unpack8(*(const v4u*)(kp + 8 * c), v + 8 * c);
;                 float ss = 0.f;
; #pragma unroll
;                 for (int d = 0; d < 32; ++d) ss = fmaf(v[d], v[d], ss);
;                 ss += pg8::shx(ss, lane, 1);
;                 const float rs = __builtin_amdgcn_rsqf(ss * (1.0f / 64.0f) + 1e-6f);
;     ...
;             const float sink = sinks[hq] * 1.4426950408889634f;
.LBB0_159:
	s_bfe_u32 s20, s29, 0x10005
	s_ashr_i32 s10, s29, 6
	s_lshl_b32 s30, s20, 3
	s_mul_i32 s21, s10, 20
	s_ashr_i32 s11, s10, 31
	s_add_i32 s31, s30, s21
	s_and_b32 s16, s29, 31
	s_lshl_b64 s[12:13], s[10:11], 12
	s_add_i32 s10, s31, s28
	s_lshl_b32 s18, s16, 7
	s_ashr_i32 s11, s10, 31
	s_or_b32 s17, s12, s18
	s_lshl_b64 s[10:11], s[10:11], 12
	v_mov_b32_e32 v1, s13
	v_or_b32_e32 v0, s17, v118
	v_mov_b32_e32 v3, s11
	v_or_b32_e32 v2, s10, v118
	v_readlane_b32 s10, v253, 2
	v_or_b32_e32 v2, s18, v2
	v_lshlrev_b64 v[0:1], 6, v[0:1]
	v_readlane_b32 s11, v253, 3
	v_lshlrev_b64 v[2:3], 7, v[2:3]
	s_waitcnt lgkmcnt(0)
	v_lshl_add_u64 v[124:125], s[10:11], 0, v[0:1]
	s_barrier
	v_lshl_add_u64 v[16:17], v[112:113], 0, v[2:3]
	global_load_dwordx4 v[12:15], v[124:125], off offset:48
	global_load_dwordx4 v[8:11], v[124:125], off offset:32
	global_load_dwordx4 v[0:3], v[124:125], off offset:16
	global_load_dwordx4 v[4:7], v[124:125], off
	global_load_dwordx4 v[80:83], v[16:17], off
	global_load_dwordx4 v[84:87], v[16:17], off offset:32
	global_load_dwordx4 v[88:91], v[16:17], off offset:64
	global_load_dwordx4 v[92:95], v[16:17], off offset:96
	s_lshr_b32 s14, s99, 2
	s_add_i32 s14, s14, s30
	s_ashr_i32 s15, s14, 31
	s_lshl_b64 s[14:15], s[14:15], 2
	s_add_u32 s14, s27, s14
	s_addc_u32 s15, s88, s15
	v_mbcnt_lo_u32_b32 v237, -1, 0
	v_mbcnt_hi_u32_b32 v237, -1, v237
	v_and_b32_e32 v237, 3, v237
	v_lshlrev_b32_e32 v237, 3, v237
	global_load_dword v236, v237, s[14:15]
	s_add_i32 s34, s18, 0xffffff80
	v_add_u32_e32 v156, s34, v119
	s_mov_b32 s19, s13
	v_cmp_lt_i32_e32 vcc, -1, v156
	v_mov_b32_e32 v19, 0
	v_mov_b32_e32 v18, 0
	v_mov_b32_e32 v17, 0
	v_mov_b32_e32 v16, 0
	v_mov_b32_e32 v23, 0
	v_mov_b32_e32 v22, 0
	v_mov_b32_e32 v21, 0
	v_mov_b32_e32 v20, 0
	v_mov_b32_e32 v27, 0
	v_mov_b32_e32 v26, 0
	v_mov_b32_e32 v25, 0
	v_mov_b32_e32 v24, 0
	v_mov_b32_e32 v31, 0
	v_mov_b32_e32 v30, 0
	v_mov_b32_e32 v29, 0
	v_mov_b32_e32 v28, 0
	s_and_saveexec_b64 s[10:11], vcc
	s_cbranch_execz .LBB0_163
	s_add_i32 s14, s21, s20
	s_add_i32 s14, s14, 16
	s_ashr_i32 s15, s14, 31
	s_lshl_b64 s[14:15], s[14:15], 19
	s_add_u32 s14, s90, s14
	s_addc_u32 s15, s91, s15
	v_lshlrev_b64 v[16:17], 7, v[156:157]
	v_lshl_add_u64 v[16:17], s[14:15], 0, v[16:17]
	v_mov_b32_e32 v123, v157
	v_lshl_add_u64 v[16:17], v[16:17], 0, v[122:123]
	global_load_dwordx4 v[32:35], v[16:17], off offset:48
	global_load_dwordx4 v[36:39], v[16:17], off offset:32
	global_load_dwordx4 v[56:59], v[16:17], off offset:16
	global_load_dwordx4 v[46:49], v[16:17], off
	ds_read_b128 v[28:31], v129
	ds_read_b128 v[24:27], v129 offset:16
	ds_read_b128 v[20:23], v129 offset:32
	ds_read_b128 v[16:19], v129 offset:48
	s_waitcnt vmcnt(0)
	ds_read_b128 v[62:65], v129 offset:64
	ds_read_b128 v[68:71], v129 offset:80
	s_waitcnt lgkmcnt(4)
	v_mov_b32_e32 v43, v27
	ds_read_b128 v[72:75], v129 offset:96
	s_waitcnt lgkmcnt(3)
	v_mov_b32_e32 v42, v19
	s_waitcnt lgkmcnt(2)
	v_mov_b32_e32 v19, v62
	v_mov_b32_e32 v60, v63
	v_mov_b32_e32 v61, v64
	s_waitcnt lgkmcnt(1)
	v_pk_mov_b32 v[66:67], v[64:65], v[68:69] op_sel:[1,0]
	v_mov_b32_e32 v68, v69
	v_mov_b32_e32 v69, v70
	s_waitcnt vmcnt(3)
	v_lshlrev_b32_e32 v77, 16, v32
	s_waitcnt vmcnt(2)
	v_and_b32_e32 v62, 0xffff0000, v37
	s_waitcnt vmcnt(1)
	v_lshlrev_b32_e32 v44, 16, v56
	s_waitcnt vmcnt(0)
	v_lshlrev_b32_e32 v50, 16, v46
	v_and_b32_e32 v51, 0xffff0000, v46
	v_fma_f32 v27, v50, v50, 0
	v_fmac_f32_e32 v27, v51, v51
	v_lshlrev_b32_e32 v52, 16, v47
	v_and_b32_e32 v53, 0xffff0000, v47
	v_fmac_f32_e32 v27, v52, v52
	v_fmac_f32_e32 v27, v53, v53
	v_lshlrev_b32_e32 v54, 16, v48
	v_and_b32_e32 v55, 0xffff0000, v48
	v_fmac_f32_e32 v27, v54, v54
	v_lshlrev_b32_e32 v102, 16, v49
	v_fmac_f32_e32 v27, v55, v55
	v_and_b32_e32 v41, 0xffff0000, v49
	v_fmac_f32_e32 v27, v102, v102
	v_fmac_f32_e32 v27, v41, v41
	v_and_b32_e32 v45, 0xffff0000, v56
	v_fmac_f32_e32 v27, v44, v44
	v_lshlrev_b32_e32 v46, 16, v57
	v_fmac_f32_e32 v27, v45, v45
	v_and_b32_e32 v47, 0xffff0000, v57
	v_fmac_f32_e32 v27, v46, v46
	v_lshlrev_b32_e32 v48, 16, v58
	v_fmac_f32_e32 v27, v47, v47
	v_and_b32_e32 v49, 0xffff0000, v58
	v_fmac_f32_e32 v27, v48, v48
	v_fmac_f32_e32 v27, v49, v49
	v_lshlrev_b32_e32 v56, 16, v59
	v_and_b32_e32 v40, 0xffff0000, v59
	v_fmac_f32_e32 v27, v56, v56
	v_lshlrev_b32_e32 v57, 16, v36
	v_fmac_f32_e32 v27, v40, v40
	v_fmac_f32_e32 v27, v57, v57
	v_and_b32_e32 v58, 0xffff0000, v36
	v_lshlrev_b32_e32 v59, 16, v37
	v_fmac_f32_e32 v27, v58, v58
	v_fmac_f32_e32 v27, v59, v59
	v_lshlrev_b32_e32 v63, 16, v38
	v_fmac_f32_e32 v27, v62, v62
	v_fmac_f32_e32 v27, v63, v63
	v_and_b32_e32 v64, 0xffff0000, v38
	v_lshlrev_b32_e32 v65, 16, v39
	v_fmac_f32_e32 v27, v64, v64
	v_fmac_f32_e32 v27, v65, v65
	v_and_b32_e32 v76, 0xffff0000, v39
	v_fmac_f32_e32 v27, v76, v76
	ds_read_b128 v[36:39], v129 offset:112
	v_fmac_f32_e32 v27, v77, v77
	v_and_b32_e32 v78, 0xffff0000, v32
	v_lshlrev_b32_e32 v79, 16, v33
	v_fmac_f32_e32 v27, v78, v78
	v_fmac_f32_e32 v27, v79, v79
	v_and_b32_e32 v104, 0xffff0000, v33
	v_lshlrev_b32_e32 v105, 16, v34
	v_fmac_f32_e32 v27, v104, v104
	s_waitcnt lgkmcnt(1)
; __device__ __forceinline__ float shx(float v, int lane, int m) { return __builtin_bit_cast(float, __builtin_amdgcn_ds_bpermute((lane ^ m) << 2, __builtin_bit_cast(int, v))); }
; #define LAS __attribute__((address_space(3)))
; __device__ __forceinline__ void sw_attn(const bf16* QKV, const float* rope, const float* qg, const float* kg, const float* sinks, bf16* O, LAS unsigned char* lds, int tid) {
;     ...
;                 float ss = 0.f;
; #pragma unroll
;                 for (int d = 0; d < 32; ++d) ss = fmaf(v[d], v[d], ss);
;                 ss += pg8::shx(ss, lane, 1);
;                 const float rs = __builtin_amdgcn_rsqf(ss * (1.0f / 64.0f) + 1e-6f);
; #pragma unroll
;                 for (int d4 = 0; d4 < 8; ++d4) { const f32x4 g4 = *(const LAS f32x4*)(gtab + 64 + 32 * half + 4 * d4); v[4 * d4] *= rs * g4[0]; v[4 * d4 + 1] *= rs * g4[1]; v[4 * d4 + 2] *= rs * g4[2]; v[4 * d4 + 3] *= rs * g4[3]; }
;                 if (half == 0) { const f32x4* rp4 = (const f32x4*)(rope + (tok0 + kpos) * 16); const f32x4 c0 = rp4[0], c1 = rp4[1], s0 = rp4[2], s1 = rp4[3];
; #pragma unroll
;                     for (int i = 0; i < 8; ++i) { const float c = i < 4 ? c0[i & 3] : c1[i & 3], sn = i < 4 ? s0[i & 3] : s1[i & 3], x1 = v[i], x2 = v[8 + i]; v[i] = x1 * c - x2 * sn; v[8 + i] = x2 * c + x1 * sn; } }
	v_mov_b32_e32 v99, v74
	v_fmac_f32_e32 v27, v105, v105
	s_waitcnt lgkmcnt(0)
	v_pk_mov_b32 v[106:107], v[74:75], v[36:37] op_sel:[1,0]
	v_and_b32_e32 v74, 0xffff0000, v34
	v_lshlrev_b32_e32 v75, 16, v35
	v_fmac_f32_e32 v27, v74, v74
	v_and_b32_e32 v101, 0xffff0000, v35
	v_fmac_f32_e32 v27, v75, v75
	v_fmac_f32_e32 v27, v101, v101
	ds_bpermute_b32 v32, v121, v27
	v_pk_mov_b32 v[96:97], v[70:71], v[72:73] op_sel:[1,0]
	v_mov_b32_e32 v98, v73
	s_waitcnt lgkmcnt(0)
	v_add_f32_e32 v27, v27, v32
	v_fmamk_f32 v27, v27, 0x3c800000, v232
	v_rsq_f32_e32 v100, v27
	s_nop 0
	v_pk_mul_f32 v[28:29], v[28:29], v[100:101] op_sel_hi:[1,0]
	s_nop 0
	v_pk_mul_f32 v[72:73], v[28:29], v[50:51]
	v_pk_mul_f32 v[28:29], v[30:31], v[100:101] op_sel_hi:[1,0]
	v_pk_mul_f32 v[24:25], v[24:25], v[100:101] op_sel_hi:[1,0]
	v_pk_mul_f32 v[70:71], v[28:29], v[52:53]
	v_pk_mul_f32 v[52:53], v[24:25], v[54:55]
	v_mul_f32_e32 v24, v26, v100
	v_pk_mul_f32 v[26:27], v[42:43], v[100:101] op_sel_hi:[1,0]
	v_pk_mul_f32 v[16:17], v[16:17], v[100:101] op_sel_hi:[1,0]
	v_pk_mul_f32 v[50:51], v[26:27], v[40:41]
	v_pk_mul_f32 v[26:27], v[16:17], v[48:49]
	v_pk_mul_f32 v[16:17], v[18:19], v[100:101] op_sel_hi:[1,0]
	v_pk_mul_f32 v[20:21], v[20:21], v[100:101] op_sel_hi:[1,0]
	v_pk_mul_f32 v[28:29], v[16:17], v[56:57]
	v_pk_mul_f32 v[16:17], v[60:61], v[100:101] op_sel_hi:[1,0]
	v_pk_mul_f32 v[20:21], v[20:21], v[44:45]
	v_pk_mul_f32 v[30:31], v[16:17], v[58:59]
	v_pk_mul_f32 v[16:17], v[66:67], v[100:101] op_sel_hi:[1,0]
	v_pk_mul_f32 v[22:23], v[22:23], v[100:101] op_sel_hi:[1,0]
	v_pk_mul_f32 v[32:33], v[16:17], v[62:63]
	v_pk_mul_f32 v[16:17], v[68:69], v[100:101] op_sel_hi:[1,0]
	v_mul_f32_e32 v24, v24, v102
	v_pk_mul_f32 v[34:35], v[16:17], v[64:65]
	v_pk_mul_f32 v[16:17], v[96:97], v[100:101] op_sel_hi:[1,0]
	v_pk_mul_f32 v[22:23], v[22:23], v[46:47]
	v_pk_mul_f32 v[40:41], v[16:17], v[76:77]
	v_pk_mul_f32 v[16:17], v[98:99], v[100:101] op_sel_hi:[1,0]
	s_nop 0
	v_pk_mul_f32 v[42:43], v[16:17], v[78:79]
	v_pk_mul_f32 v[16:17], v[106:107], v[100:101] op_sel_hi:[1,0]
	s_nop 0
	v_pk_mul_f32 v[44:45], v[16:17], v[104:105]
	v_mov_b32_e32 v16, v37
	v_mov_b32_e32 v17, v38
	v_pk_mul_f32 v[16:17], v[16:17], v[100:101] op_sel_hi:[1,0]
	s_nop 0
	v_pk_mul_f32 v[36:37], v[16:17], v[74:75]
	v_mul_f32_e32 v16, v39, v100
	v_mul_f32_e32 v38, v16, v101
	s_mov_b64 s[14:15], exec
	v_readlane_b32 vcc_lo, v252, 0
	v_readlane_b32 vcc_hi, v252, 1
	s_and_b64 vcc, s[14:15], vcc
	s_mov_b64 exec, vcc
	s_cbranch_execz .LBB0_162
	v_lshl_add_u64 v[16:17], s[12:13], 0, v[156:157]
	v_readlane_b32 s12, v253, 2
	v_lshlrev_b64 v[16:17], 6, v[16:17]
	v_readlane_b32 s13, v253, 3
	v_mov_b32_e32 v25, v51
	s_nop 0
	v_lshl_add_u64 v[58:59], s[12:13], 0, v[16:17]
	global_load_dwordx4 v[16:19], v[58:59], off offset:48
	global_load_dwordx4 v[46:49], v[58:59], off offset:16
	global_load_dwordx4 v[54:57], v[58:59], off offset:32
	s_nop 0
	global_load_dwordx4 v[58:61], v[58:59], off
	s_waitcnt vmcnt(1)
	v_pk_mul_f32 v[62:63], v[20:21], v[54:55]
	v_pk_mul_f32 v[54:55], v[72:73], v[54:55]
	s_waitcnt vmcnt(0)
	v_pk_fma_f32 v[62:63], v[72:73], v[58:59], v[62:63] neg_lo:[0,0,1] neg_hi:[0,0,1]
	v_pk_fma_f32 v[20:21], v[20:21], v[58:59], v[54:55]
	v_pk_mul_f32 v[54:55], v[22:23], v[56:57]
	v_pk_mul_f32 v[56:57], v[70:71], v[56:57]
	v_pk_fma_f32 v[54:55], v[70:71], v[60:61], v[54:55] neg_lo:[0,0,1] neg_hi:[0,0,1]
	v_pk_fma_f32 v[22:23], v[22:23], v[60:61], v[56:57]
	v_pk_mul_f32 v[56:57], v[26:27], v[16:17]
	v_pk_mul_f32 v[16:17], v[52:53], v[16:17]
	v_pk_fma_f32 v[56:57], v[52:53], v[46:47], v[56:57] neg_lo:[0,0,1] neg_hi:[0,0,1]
	v_mov_b32_e32 v52, v28
	v_mov_b32_e32 v53, v50
	v_pk_fma_f32 v[26:27], v[26:27], v[46:47], v[16:17]
	v_mul_f32_e32 v46, v24, v18
	v_pk_mul_f32 v[52:53], v[52:53], v[18:19]
	v_mov_b32_e32 v18, v49
	v_pk_mul_f32 v[18:19], v[50:51], v[18:19]
	v_mul_f32_e32 v16, v28, v48
	v_mov_b32_e32 v17, v18
	v_mov_b32_e32 v47, v19
	v_pk_fma_f32 v[24:25], v[24:25], v[48:49], v[52:53] neg_lo:[0,0,1] neg_hi:[0,0,1]
	v_pk_add_f32 v[16:17], v[16:17], v[46:47]
	v_mov_b32_e32 v72, v62
	v_mov_b32_e32 v73, v63
	v_mov_b32_e32 v70, v54
	v_mov_b32_e32 v71, v55
	v_mov_b32_e32 v52, v56
	v_mov_b32_e32 v53, v57
	v_mov_b32_e32 v51, v25
	v_mov_b32_e32 v28, v16
	v_mov_b32_e32 v50, v17

; #define LAS __attribute__((address_space(3)))
; __device__ __forceinline__ unsigned cvtpk(float lo, float hi) { f32x2_t v = {lo, hi}; bf16x2_t b = __builtin_convertvector(v, bf16x2_t); return __builtin_bit_cast(unsigned, b); }
; __device__ __forceinline__ void unpack8(const v4u w, float* v) { v[0] = bf_lo(w.x); v[1] = bf_hi(w.x); v[2] = bf_lo(w.y); v[3] = bf_hi(w.y); v[4] = bf_lo(w.z); v[5] = bf_hi(w.z); v[6] = bf_lo(w.w); v[7] = bf_hi(w.w); }
; __device__ __forceinline__ void sw_attn(const bf16* QKV, const float* rope, const float* qg, const float* kg, const float* sinks, bf16* O, LAS unsigned char* lds, int tid) {
;     ...
;                 float qv[4][8]; float ss = 0.f;
; #pragma unroll
;                 for (int ks = 0; ks < 4; ++ks) { unpack8(qraw[ks], qv[ks]);
; #pragma unroll
;                     for (int i = 0; i < 8; ++i) ss = fmaf(qv[ks][i], qv[ks][i], ss); }
;                 { float lo_, up_; halves(ss, lo_, up_); ss = lo_ + up_; }
;                 const float rs = __builtin_amdgcn_rsqf(ss * (1.0f / 64.0f) + 1e-6f);
; #pragma unroll
;                 for (int ks = 0; ks < 4; ++ks) { const f32x4 g0 = *(const LAS f32x4*)(gtab + 16 * ks + 8 * hi), g1 = *(const LAS f32x4*)(gtab + 16 * ks + 8 * hi + 4);
; #pragma unroll
;                     for (int i = 0; i < 8; ++i) qv[ks][i] = qv[ks][i] * rs * (i < 4 ? g0[i & 3] : g1[i & 3]); }
; #pragma unroll
;                 for (int i = 0; i < 8; ++i) { float lo_, up_; const float own = qv[0][i]; halves(own, lo_, up_); const float oth = hi ? lo_ : up_, c = i < 4 ? rraw[0][i & 3] : rraw[1][i & 3], sn = i < 4 ? rraw[2][i & 3] : rraw[3][i & 3]; qv[0][i] = own * c + oth * (hi ? sn : -sn); }
; #pragma unroll
;                 for (int ks = 0; ks < 4; ++ks) { const v4u w = {cvtpk(qv[ks][0] * QS, qv[ks][1] * QS), cvtpk(qv[ks][2] * QS, qv[ks][3] * QS), cvtpk(qv[ks][4] * QS, qv[ks][5] * QS), cvtpk(qv[ks][6] * QS, qv[ks][7] * QS)}; qf[ks] = __builtin_bit_cast(bf16x8, w); }
;             }
;             if (p < 3) SW_LOADQ(p + 1);
;             const float sink = sinks[hq] * 1.4426950408889634f;
.LBB0_174:
	v_lshlrev_b32_e32 v30, 16, v80
	v_and_b32_e32 v31, 0xffff0000, v80
	v_fma_f32 v16, v30, v30, 0
	v_lshlrev_b32_e32 v28, 16, v81
	v_fmac_f32_e32 v16, v31, v31
	v_and_b32_e32 v29, 0xffff0000, v81
	v_fmac_f32_e32 v16, v28, v28
	v_lshlrev_b32_e32 v26, 16, v82
	v_fmac_f32_e32 v16, v29, v29
	v_and_b32_e32 v27, 0xffff0000, v82
	v_fmac_f32_e32 v16, v26, v26
	v_lshlrev_b32_e32 v24, 16, v83
	v_fmac_f32_e32 v16, v27, v27
	v_and_b32_e32 v25, 0xffff0000, v83
	v_fmac_f32_e32 v16, v24, v24
	v_lshlrev_b32_e32 v62, 16, v84
	v_fmac_f32_e32 v16, v25, v25
	v_and_b32_e32 v63, 0xffff0000, v84
	v_fmac_f32_e32 v16, v62, v62
	v_lshlrev_b32_e32 v60, 16, v85
	v_fmac_f32_e32 v16, v63, v63
	v_and_b32_e32 v61, 0xffff0000, v85
	v_fmac_f32_e32 v16, v60, v60
	v_lshlrev_b32_e32 v58, 16, v86
	v_fmac_f32_e32 v16, v61, v61
	v_and_b32_e32 v59, 0xffff0000, v86
	v_fmac_f32_e32 v16, v58, v58
	v_lshlrev_b32_e32 v56, 16, v87
	v_fmac_f32_e32 v16, v59, v59
	v_and_b32_e32 v57, 0xffff0000, v87
	v_fmac_f32_e32 v16, v56, v56
	v_lshlrev_b32_e32 v54, 16, v88
	v_fmac_f32_e32 v16, v57, v57
	v_and_b32_e32 v55, 0xffff0000, v88
	v_fmac_f32_e32 v16, v54, v54
	v_lshlrev_b32_e32 v52, 16, v89
	v_fmac_f32_e32 v16, v55, v55
	v_and_b32_e32 v53, 0xffff0000, v89
	v_fmac_f32_e32 v16, v52, v52
	v_lshlrev_b32_e32 v50, 16, v90
	v_fmac_f32_e32 v16, v53, v53
	v_and_b32_e32 v51, 0xffff0000, v90
	v_fmac_f32_e32 v16, v50, v50
	v_lshlrev_b32_e32 v48, 16, v91
	v_fmac_f32_e32 v16, v51, v51
	v_and_b32_e32 v49, 0xffff0000, v91
	v_fmac_f32_e32 v16, v48, v48
	v_lshlrev_b32_e32 v46, 16, v92
	v_fmac_f32_e32 v16, v49, v49
	v_and_b32_e32 v47, 0xffff0000, v92
	v_fmac_f32_e32 v16, v46, v46
	v_lshlrev_b32_e32 v44, 16, v93
	v_fmac_f32_e32 v16, v47, v47
	v_and_b32_e32 v45, 0xffff0000, v93
	v_fmac_f32_e32 v16, v44, v44
	v_lshlrev_b32_e32 v42, 16, v94
	v_fmac_f32_e32 v16, v45, v45
	v_and_b32_e32 v43, 0xffff0000, v94
	v_fmac_f32_e32 v16, v42, v42
	v_lshlrev_b32_e32 v40, 16, v95
	v_fmac_f32_e32 v16, v43, v43
	v_and_b32_e32 v41, 0xffff0000, v95
	v_fmac_f32_e32 v16, v40, v40
	v_fmac_f32_e32 v16, v41, v41
	v_mov_b32_e32 v17, v16
	ds_read_b128 v[20:23], v131 offset:16
	s_nop 0
	v_permlane32_swap_b32_e32 v16, v17
	v_add_f32_e32 v16, v16, v17
	v_fmamk_f32 v16, v16, 0x3c800000, v232
	v_rsq_f32_e32 v68, v16
	ds_read_b128 v[16:19], v131
	s_add_i32 s18, s99, s34
	s_lshr_b32 s21, s34, 3
	s_nop 3
	v_readlane_b32 s20, v236, s21
	s_nop 1
	v_mov_b32_e32 v238, s20
	s_cmp_eq_u32 s34, 24
	v_pk_mul_f32 v[30:31], v[68:69], v[30:31] op_sel_hi:[0,1]
	s_waitcnt lgkmcnt(0)
	v_pk_mul_f32 v[70:71], v[16:17], v[30:31]
	v_pk_mul_f32 v[16:17], v[68:69], v[28:29] op_sel_hi:[0,1]
	v_pk_mul_f32 v[72:73], v[18:19], v[16:17]
	v_pk_mul_f32 v[16:17], v[68:69], v[26:27] op_sel_hi:[0,1]
	v_pk_mul_f32 v[64:65], v[20:21], v[16:17]
	v_pk_mul_f32 v[16:17], v[68:69], v[24:25] op_sel_hi:[0,1]
	v_pk_mul_f32 v[66:67], v[22:23], v[16:17]
	ds_read_b128 v[36:39], v131 offset:64
	ds_read_b128 v[32:35], v131 offset:80
	ds_read_b128 v[28:31], v131 offset:128
	ds_read_b128 v[24:27], v131 offset:144
	ds_read_b128 v[20:23], v131 offset:192
	ds_read_b128 v[16:19], v131 offset:208
	v_mov_b32_e32 v74, v70
	v_mov_b32_e32 v76, v71
	v_mov_b32_e32 v77, v72
	v_mov_b32_e32 v123, v73
	v_mov_b32_e32 v144, v64
	v_mov_b32_e32 v147, v65
	v_mov_b32_e32 v148, v66
	v_mov_b32_e32 v151, v67
	v_mov_b32_e32 v75, v70
	v_mov_b32_e32 v78, v71
	v_mov_b32_e32 v79, v72
	v_mov_b32_e32 v145, v73
	v_mov_b32_e32 v146, v64
	v_mov_b32_e32 v149, v65
	v_mov_b32_e32 v150, v66
	v_mov_b32_e32 v152, v67
	v_permlane32_swap_b32_e32 v75, v74
	v_permlane32_swap_b32_e32 v78, v76
	v_permlane32_swap_b32_e32 v79, v77
	v_permlane32_swap_b32_e32 v145, v123
	v_permlane32_swap_b32_e32 v146, v144
	v_permlane32_swap_b32_e32 v149, v147
	v_permlane32_swap_b32_e32 v150, v148
	v_permlane32_swap_b32_e32 v152, v151
	s_cbranch_scc1 .LBB0_176
	s_add_i32 s19, s18, 8
	s_ashr_i32 s19, s19, 2
	s_add_i32 s20, s19, s31
	s_ashr_i32 s21, s20, 31
	s_lshl_b64 s[20:21], s[20:21], 19
	v_lshl_or_b32 v80, v128, 7, s20
	v_mov_b32_e32 v81, s21
	v_lshl_add_u64 v[92:93], v[112:113], 0, v[80:81]
	global_load_dwordx4 v[108:111], v[124:125], off offset:48
	global_load_dwordx4 v[104:107], v[124:125], off offset:32
	global_load_dwordx4 v[100:103], v[124:125], off offset:16
	global_load_dwordx4 v[96:99], v[124:125], off
	global_load_dwordx4 v[80:83], v[92:93], off
	global_load_dwordx4 v[84:87], v[92:93], off offset:32
	global_load_dwordx4 v[88:91], v[92:93], off offset:64
	s_nop 0
	global_load_dwordx4 v[92:95], v[92:93], off offset:96
; #define LAS __attribute__((address_space(3)))
; __device__ __forceinline__ unsigned cvtpk(float lo, float hi) { f32x2_t v = {lo, hi}; bf16x2_t b = __builtin_convertvector(v, bf16x2_t); return __builtin_bit_cast(unsigned, b); }
; #define SB_MFMA(a, b, c) __builtin_amdgcn_mfma_f32_32x32x16_bf16((a), (b), (c), 0, 0, 0)
; __device__ __forceinline__ void sw_attn(const bf16* QKV, const float* rope, const float* qg, const float* kg, const float* sinks, bf16* O, LAS unsigned char* lds, int tid) {
;     ...
;                 for (int i = 0; i < 8; ++i) { float lo_, up_; const float own = qv[0][i]; halves(own, lo_, up_); const float oth = hi ? lo_ : up_, c = i < 4 ? rraw[0][i & 3] : rraw[1][i & 3], sn = i < 4 ? rraw[2][i & 3] : rraw[3][i & 3]; qv[0][i] = own * c + oth * (hi ? sn : -sn); }
; #pragma unroll
;                 for (int ks = 0; ks < 4; ++ks) { const v4u w = {cvtpk(qv[ks][0] * QS, qv[ks][1] * QS), cvtpk(qv[ks][2] * QS, qv[ks][3] * QS), cvtpk(qv[ks][4] * QS, qv[ks][5] * QS), cvtpk(qv[ks][6] * QS, qv[ks][7] * QS)}; qf[ks] = __builtin_bit_cast(bf16x8, w); }
;             }
;             if (p < 3) SW_LOADQ(p + 1);
;             const float sink = sinks[hq] * 1.4426950408889634f;
;             f32x16 s[5]; float mx = sink;
;             const float NEG = -__builtin_inff();
; #pragma unroll
;             for (int js = 0; js < 5; ++js) {
; #pragma unroll
;                 for (int r = 0; r < 16; ++r) s[js][r] = 0.f;
;                 const bool live = !(blk == 0 && tb + js < 4);
;                 if (live) {
; #pragma unroll
;                     for (int ks = 0; ks < 4; ++ks) { const bf16x8 a = *(const LAS bf16x8*)(kl + (32 * (tb + js) + l32) * KROW + 32 * ks + 16 * hi); s[js] = SB_MFMA(a, qf[ks], s[js]); }
; #pragma unroll
;                     for (int r = 0; r < 16; ++r) {
;                         const int kk = (r & 3) + 8 * (r >> 2) + 4 * hi;
;                         float v = s[js][r];
;                         if (js == 0) v = (kk > l32) ? v : NEG;
;                         if (js == 4) v = (kk <= l32) ? v : NEG;
;                         s[js][r] = v; mx = fmaxf(mx, v);
.LBB0_176:
	v_mov_b32_e32 v69, v68
	v_pk_mul_f32 v[46:47], v[68:69], v[46:47]
	v_cndmask_b32_e64 v9, v9, -v9, s[40:41]
	s_waitcnt lgkmcnt(1)
	v_pk_mul_f32 v[46:47], v[46:47], v[20:21]
	v_pk_mul_f32 v[20:21], v[68:69], v[44:45]
	v_cndmask_b32_e64 v8, v8, -v8, s[40:41]
	v_pk_mul_f32 v[22:23], v[20:21], v[22:23]
	v_pk_mul_f32 v[20:21], v[68:69], v[42:43]
	v_cndmask_b32_e64 v11, v11, -v11, s[40:41]
	s_waitcnt lgkmcnt(0)
	v_pk_mul_f32 v[16:17], v[20:21], v[16:17]
	v_pk_mul_f32 v[20:21], v[68:69], v[40:41]
	v_cndmask_b32_e64 v10, v10, -v10, s[40:41]
	v_pk_mul_f32 v[44:45], v[20:21], v[18:19]
	v_cndmask_b32_e64 v19, v78, v76, s[40:41]
	v_cndmask_b32_e64 v18, v75, v74, s[40:41]
	v_pk_mul_f32 v[8:9], v[8:9], v[18:19]
	v_cndmask_b32_e64 v13, v13, -v13, s[40:41]
	v_pk_fma_f32 v[4:5], v[4:5], v[70:71], v[8:9]
	v_cndmask_b32_e64 v9, v145, v123, s[40:41]
	v_cndmask_b32_e64 v8, v79, v77, s[40:41]
	v_pk_mul_f32 v[8:9], v[10:11], v[8:9]
	v_cndmask_b32_e64 v12, v12, -v12, s[40:41]
	v_pk_fma_f32 v[6:7], v[6:7], v[72:73], v[8:9]
	v_cndmask_b32_e64 v9, v149, v147, s[40:41]
	v_cndmask_b32_e64 v8, v146, v144, s[40:41]
	v_pk_mul_f32 v[8:9], v[12:13], v[8:9]
	v_cndmask_b32_e64 v15, v15, -v15, s[40:41]
	v_cndmask_b32_e64 v14, v14, -v14, s[40:41]
	v_pk_fma_f32 v[0:1], v[0:1], v[64:65], v[8:9]
	v_cndmask_b32_e64 v9, v152, v151, s[40:41]
	v_cndmask_b32_e64 v8, v150, v148, s[40:41]
	v_pk_mul_f32 v[8:9], v[14:15], v[8:9]
	v_pk_mul_f32 v[62:63], v[68:69], v[62:63]
	v_pk_fma_f32 v[2:3], v[2:3], v[66:67], v[8:9]
	v_pk_mul_f32 v[0:1], v[0:1], s[74:75] op_sel_hi:[1,0]
	v_pk_mul_f32 v[36:37], v[36:37], v[62:63]
	v_pk_mul_f32 v[60:61], v[68:69], v[60:61]
	v_cvt_pk_bf16_f32 v20, v0, v1
	v_pk_mul_f32 v[0:1], v[2:3], s[74:75] op_sel_hi:[1,0]
	v_pk_mul_f32 v[38:39], v[38:39], v[60:61]
	v_pk_mul_f32 v[58:59], v[68:69], v[58:59]
	v_cvt_pk_bf16_f32 v21, v0, v1
	v_pk_mul_f32 v[0:1], v[36:37], s[74:75] op_sel_hi:[1,0]
	v_pk_mul_f32 v[32:33], v[32:33], v[58:59]
	v_pk_mul_f32 v[56:57], v[68:69], v[56:57]
	v_cvt_pk_bf16_f32 v36, v0, v1
	v_pk_mul_f32 v[0:1], v[38:39], s[74:75] op_sel_hi:[1,0]
	v_pk_mul_f32 v[34:35], v[34:35], v[56:57]
	v_pk_mul_f32 v[54:55], v[68:69], v[54:55]
	v_cvt_pk_bf16_f32 v37, v0, v1
	v_pk_mul_f32 v[0:1], v[32:33], s[74:75] op_sel_hi:[1,0]
	v_pk_mul_f32 v[28:29], v[28:29], v[54:55]
	v_pk_mul_f32 v[52:53], v[68:69], v[52:53]
	v_cvt_pk_bf16_f32 v38, v0, v1
	v_pk_mul_f32 v[0:1], v[34:35], s[74:75] op_sel_hi:[1,0]
	v_pk_mul_f32 v[30:31], v[30:31], v[52:53]
	v_pk_mul_f32 v[50:51], v[68:69], v[50:51]
	v_cvt_pk_bf16_f32 v39, v0, v1
	v_pk_mul_f32 v[0:1], v[28:29], s[74:75] op_sel_hi:[1,0]
	v_pk_mul_f32 v[24:25], v[50:51], v[24:25]
	v_pk_mul_f32 v[48:49], v[68:69], v[48:49]
	v_cvt_pk_bf16_f32 v40, v0, v1
	v_pk_mul_f32 v[0:1], v[30:31], s[74:75] op_sel_hi:[1,0]
	s_ashr_i32 s18, s18, 2
	v_pk_mul_f32 v[26:27], v[48:49], v[26:27]
	v_cvt_pk_bf16_f32 v41, v0, v1
	v_pk_mul_f32 v[0:1], v[24:25], s[74:75] op_sel_hi:[1,0]
	s_add_i32 s18, s18, s30
	v_cvt_pk_bf16_f32 v42, v0, v1
	v_pk_mul_f32 v[0:1], v[26:27], s[74:75] op_sel_hi:[1,0]
	s_ashr_i32 s19, s18, 31
	v_cvt_pk_bf16_f32 v43, v0, v1
	v_pk_mul_f32 v[0:1], v[46:47], s[74:75] op_sel_hi:[1,0]
	s_lshl_b64 s[20:21], s[18:19], 2
	v_cvt_pk_bf16_f32 v32, v0, v1
	v_pk_mul_f32 v[0:1], v[22:23], s[74:75] op_sel_hi:[1,0]
	s_add_u32 s20, s27, s20
	v_cvt_pk_bf16_f32 v33, v0, v1
	v_pk_mul_f32 v[0:1], v[16:17], s[74:75] op_sel_hi:[1,0]
	s_addc_u32 s21, s88, s21
	v_cvt_pk_bf16_f32 v34, v0, v1
	v_pk_mul_f32 v[0:1], v[44:45], s[74:75] op_sel_hi:[1,0]
	v_pk_mul_f32 v[4:5], v[4:5], s[74:75] op_sel_hi:[1,0]
	v_cvt_pk_bf16_f32 v35, v0, v1
	v_cvt_pk_bf16_f32 v18, v4, v5
	v_pk_mul_f32 v[4:5], v[6:7], s[74:75] op_sel_hi:[1,0]
	s_andn2_b64 vcc, exec, s[10:11]
	v_cvt_pk_bf16_f32 v19, v4, v5
	v_mov_b32_e32 v182, 0xff800000
	v_mov_b32_e32 v183, 0xff800000
	v_mov_b32_e32 v178, 0xff800000
	v_mov_b32_e32 v179, 0xff800000
	v_mov_b32_e32 v180, 0xff800000
	v_mov_b32_e32 v181, 0xff800000
	v_mov_b32_e32 v156, 0xff800000
	v_mov_b32_e32 v176, 0xff800000
	v_mov_b32_e32 v177, 0xff800000
	v_mov_b32_e32 v47, 0xff800000
	v_mov_b32_e32 v174, 0xff800000
	v_mov_b32_e32 v175, 0xff800000
	v_mov_b32_e32 v44, 0xff800000
	v_mov_b32_e32 v45, 0xff800000
	v_mov_b32_e32 v46, 0xff800000
	v_mov_b32_e32 v173, 0xff800000
	v_mul_f32_e32 v123, 0x3fb8aa3b, v238
	v_mov_b32_e32 v0, 0xff800000
	v_mov_b32_e32 v144, v123
	s_cbranch_vccnz .LBB0_178
	ds_read_b128 v[2:5], v134
	ds_read_b128 v[22:25], v134 offset:32
	s_waitcnt lgkmcnt(1)
	v_mfma_f32_32x32x16_bf16 v[2:17], v[2:5], v[18:21], 0
	s_waitcnt lgkmcnt(0)
	v_mfma_f32_32x32x16_bf16 v[2:17], v[22:25], v[36:39], v[2:17]
	ds_read_b128 v[22:25], v134 offset:64
	s_waitcnt lgkmcnt(0)
	v_mfma_f32_32x32x16_bf16 v[2:17], v[22:25], v[40:43], v[2:17]
	ds_read_b128 v[22:25], v134 offset:96
	s_waitcnt lgkmcnt(0)
	v_mfma_f32_32x32x16_bf16 v[2:17], v[22:25], v[32:35], v[2:17]
	s_nop 11
	v_cndmask_b32_e64 v182, v234, v2, s[42:43]
	v_cndmask_b32_e64 v183, v3, v234, s[44:45]
	v_cndmask_b32_e64 v178, v234, v4, s[46:47]
	v_cndmask_b32_e64 v179, v234, v5, s[48:49]
	v_max3_f32 v1, v123, v182, v183
	v_cndmask_b32_e64 v180, v234, v6, s[50:51]
	v_cndmask_b32_e64 v181, v234, v7, s[52:53]
	v_max3_f32 v1, v1, v178, v179
	v_cndmask_b32_e64 v156, v234, v8, s[54:55]
	v_cndmask_b32_e64 v176, v234, v9, s[56:57]
	v_max3_f32 v1, v1, v180, v181
	v_cndmask_b32_e64 v177, v234, v10, s[58:59]
	v_cndmask_b32_e64 v47, v234, v11, s[60:61]
	v_max3_f32 v1, v1, v156, v176
	v_cndmask_b32_e64 v174, v234, v12, s[62:63]
	v_cndmask_b32_e64 v175, v234, v13, s[64:65]
	v_max3_f32 v1, v1, v177, v47
	v_cndmask_b32_e64 v44, v234, v14, s[66:67]
	v_cndmask_b32_e64 v45, v234, v15, s[68:69]
	v_max3_f32 v1, v1, v174, v175
	v_cndmask_b32_e64 v46, v234, v16, s[70:71]
	v_max3_f32 v1, v1, v44, v45
	v_cndmask_b32_e64 v173, v234, v17, s[72:73]
	v_max3_f32 v144, v1, v46, v173
